# idle-tail w_ff1 conversion: the shift-table LDS reads of the fused bias sums issued per group with counted waits (was one LDS round trip per two FMAs)
# speedup vs baseline: 1.0063x; 1.0004x over previous
; __device__ __forceinline__ void transpose_item(const float* W, int K, int N, int NP, bf16* WT, LAS float* scr, int item, int lane, const LAS float* tab, long long* bias, int ldb, const float* kscale = nullptr) {
;     const int nblk = NP / 32, kb = item / nblk, nb = item - kb * nblk, k0 = 64 * kb, n0 = 32 * nb;
;     const int n = n0 + (lane & 31); const bool okn = n < N;
;     float wv_[32];
;     const float* wp = W + (size_t)(k0 + (lane >> 5)) * N + (okn ? n : 0);
; #pragma unroll
;     for (int i = 0; i < 32; ++i) wv_[i] = wp[(size_t)(2 * i) * N];
.LBB0_471:
	s_ashr_i32 s4, s12, 31
	s_lshr_b32 s4, s4, 24
	s_add_i32 s14, s12, s4
	s_ashr_i32 s4, s14, 8
	s_lshl_b32 s11, s4, 13
	s_lshl_b32 s10, s4, 6
	s_sub_i32 s4, s13, s11
	v_add_u32_e32 v4, s4, v1
	v_or_b32_e32 v6, s10, v8
	v_cmp_gt_i32_e32 vcc, s93, v4
	v_ashrrev_i32_e32 v7, 31, v6
	v_lshlrev_b64 v[6:7], 15, v[6:7]
	v_cndmask_b32_e32 v14, 0, v4, vcc
	v_lshl_add_u64 v[6:7], s[6:7], 0, v[6:7]
	v_ashrrev_i32_e32 v15, 31, v14
	v_lshl_add_u64 v[6:7], v[14:15], 2, v[6:7]
	v_add_co_u32_e64 v14, s[4:5], s92, v6
	global_load_dword v5, v[6:7], off
	s_nop 0
	v_addc_co_u32_e64 v15, s[4:5], 0, v7, s[4:5]
	global_load_dword v43, v[14:15], off
	v_add_co_u32_e64 v14, s[4:5], s78, v6
	v_add_u32_e32 v75, 0x1c00, v13
	s_nop 0
	v_addc_co_u32_e64 v15, s[4:5], 0, v7, s[4:5]
	global_load_dword v42, v[14:15], off
	v_add_co_u32_e64 v14, s[4:5], s49, v6
	s_nop 1
	v_addc_co_u32_e64 v15, s[4:5], 0, v7, s[4:5]
	global_load_dword v41, v[14:15], off
	v_add_co_u32_e64 v14, s[4:5], s79, v6
	s_nop 1
	v_addc_co_u32_e64 v15, s[4:5], 0, v7, s[4:5]
	global_load_dword v40, v[14:15], off
	v_add_co_u32_e64 v14, s[4:5], s0, v6
	s_nop 1
	v_addc_co_u32_e64 v15, s[4:5], 0, v7, s[4:5]
	s_mov_b32 s4, 0x60000
	global_load_dword v39, v[14:15], off
	v_add_co_u32_e64 v14, s[4:5], s4, v6
	s_nop 0
	s_nop 0
	v_addc_co_u32_e64 v15, s[4:5], 0, v7, s[4:5]
	global_load_dword v38, v[14:15], off
	v_add_co_u32_e64 v14, s[4:5], s96, v6
	s_nop 0
	s_nop 0
	v_addc_co_u32_e64 v15, s[4:5], 0, v7, s[4:5]
	s_mov_b32 s4, 0x80000
	global_load_dword v37, v[14:15], off
	v_add_co_u32_e64 v14, s[4:5], s4, v6
	s_nop 0
	s_nop 0
	v_addc_co_u32_e64 v15, s[4:5], 0, v7, s[4:5]
	s_mov_b32 s4, 0x90000
	global_load_dword v36, v[14:15], off
	v_add_co_u32_e64 v14, s[4:5], s4, v6
	s_nop 1
	v_addc_co_u32_e64 v15, s[4:5], 0, v7, s[4:5]
	s_mov_b32 s4, 0xa0000
	global_load_dword v35, v[14:15], off
	v_add_co_u32_e64 v14, s[4:5], s4, v6
	s_nop 1
	v_addc_co_u32_e64 v15, s[4:5], 0, v7, s[4:5]
	s_mov_b32 s4, 0xb0000
	global_load_dword v34, v[14:15], off
	v_add_co_u32_e64 v14, s[4:5], s4, v6
	s_nop 1
	v_addc_co_u32_e64 v15, s[4:5], 0, v7, s[4:5]
	s_mov_b32 s4, 0xc0000
	global_load_dword v32, v[14:15], off
	v_add_co_u32_e64 v14, s[4:5], s4, v6
	s_nop 1
	v_addc_co_u32_e64 v15, s[4:5], 0, v7, s[4:5]
	s_mov_b32 s4, 0xd0000
	global_load_dword v31, v[14:15], off
	v_add_co_u32_e64 v14, s[4:5], s4, v6
	s_nop 1
	v_addc_co_u32_e64 v15, s[4:5], 0, v7, s[4:5]
	s_mov_b32 s4, 0xe0000
	global_load_dword v30, v[14:15], off
	v_add_co_u32_e64 v14, s[4:5], s4, v6
	s_nop 1
	v_addc_co_u32_e64 v15, s[4:5], 0, v7, s[4:5]
	s_mov_b32 s4, 0xf0000
	global_load_dword v29, v[14:15], off
	v_add_co_u32_e64 v14, s[4:5], s4, v6
	s_nop 0
	s_nop 0
	v_addc_co_u32_e64 v15, s[4:5], 0, v7, s[4:5]
	s_mov_b32 s4, 0x100000
	global_load_dword v28, v[14:15], off
	v_add_co_u32_e64 v14, s[4:5], s4, v6
	s_nop 0
	s_nop 0
	v_addc_co_u32_e64 v15, s[4:5], 0, v7, s[4:5]
	s_mov_b32 s4, 0x110000
	global_load_dword v27, v[14:15], off
	v_add_co_u32_e64 v14, s[4:5], s4, v6
	s_nop 0
	s_nop 0
	v_addc_co_u32_e64 v15, s[4:5], 0, v7, s[4:5]
	s_mov_b32 s4, 0x120000
	global_load_dword v26, v[14:15], off
	v_add_co_u32_e64 v14, s[4:5], s4, v6
	s_nop 0
	s_nop 0
	v_addc_co_u32_e64 v15, s[4:5], 0, v7, s[4:5]
	s_mov_b32 s4, 0x130000
	global_load_dword v25, v[14:15], off
	v_add_co_u32_e64 v14, s[4:5], s4, v6
	s_nop 0
	s_nop 0
	v_addc_co_u32_e64 v15, s[4:5], 0, v7, s[4:5]
	s_mov_b32 s4, 0x140000
	global_load_dword v24, v[14:15], off
	v_add_co_u32_e64 v14, s[4:5], s4, v6
	s_nop 0
	s_nop 0
	v_addc_co_u32_e64 v15, s[4:5], 0, v7, s[4:5]
	s_mov_b32 s4, 0x150000
	global_load_dword v23, v[14:15], off
	v_add_co_u32_e64 v14, s[4:5], s4, v6
	s_nop 1
	v_addc_co_u32_e64 v15, s[4:5], 0, v7, s[4:5]
	s_mov_b32 s4, 0x160000
	global_load_dword v22, v[14:15], off
	v_add_co_u32_e64 v14, s[4:5], s4, v6
	s_nop 1
	v_addc_co_u32_e64 v15, s[4:5], 0, v7, s[4:5]
	s_mov_b32 s4, 0x170000
	global_load_dword v21, v[14:15], off
	v_add_co_u32_e64 v14, s[4:5], s4, v6
	s_nop 1
	v_addc_co_u32_e64 v15, s[4:5], 0, v7, s[4:5]
	s_mov_b32 s4, 0x180000
	global_load_dword v20, v[14:15], off
	v_add_co_u32_e64 v14, s[4:5], s4, v6
	s_nop 1
	v_addc_co_u32_e64 v15, s[4:5], 0, v7, s[4:5]
	s_mov_b32 s4, 0x190000
	global_load_dword v19, v[14:15], off
	v_add_co_u32_e64 v14, s[4:5], s4, v6
	s_nop 1
	v_addc_co_u32_e64 v15, s[4:5], 0, v7, s[4:5]
	s_mov_b32 s4, 0x1a0000
	global_load_dword v18, v[14:15], off
	v_add_co_u32_e64 v14, s[4:5], s4, v6
	s_nop 1
	v_addc_co_u32_e64 v15, s[4:5], 0, v7, s[4:5]
	s_mov_b32 s4, 0x1b0000
	global_load_dword v17, v[14:15], off
	v_add_co_u32_e64 v14, s[4:5], s4, v6
	s_nop 1
	v_addc_co_u32_e64 v15, s[4:5], 0, v7, s[4:5]
	s_mov_b32 s4, 0x1c0000
	global_load_dword v16, v[14:15], off
	v_add_co_u32_e64 v14, s[4:5], s4, v6
	s_nop 1
	v_addc_co_u32_e64 v15, s[4:5], 0, v7, s[4:5]
	s_mov_b32 s4, 0x1d0000
	global_load_dword v44, v[14:15], off
	v_add_co_u32_e64 v14, s[4:5], s4, v6
	s_nop 1
	v_addc_co_u32_e64 v15, s[4:5], 0, v7, s[4:5]
	s_mov_b32 s4, 0x1e0000
	global_load_dword v45, v[14:15], off
	v_add_co_u32_e64 v14, s[4:5], s4, v6
	s_nop 1
	v_addc_co_u32_e64 v15, s[4:5], 0, v7, s[4:5]
	s_mov_b32 s4, 0x1f0000
	s_nop 0
	v_add_co_u32_e64 v6, s[4:5], s4, v6
	global_load_dword v14, v[14:15], off
	s_nop 0
	v_addc_co_u32_e64 v7, s[4:5], 0, v7, s[4:5]
	global_load_dword v7, v[6:7], off
	s_waitcnt vmcnt(0)
; #define LAS __attribute__((address_space(3)))
; __device__ __forceinline__ void transpose_item(const float* W, int K, int N, int NP, bf16* WT, LAS float* scr, int item, int lane, const LAS float* tab, long long* bias, int ldb, const float* kscale = nullptr) {
;     ...
;     for (int i = 0; i < 32; ++i) { if (!okn) wv_[i] = 0.f; if (kscale != nullptr) wv_[i] *= kscale[k0 + 2 * i + (lane >> 5)]; scr[(2 * i + (lane >> 5)) * 33 + (lane & 31)] = wv_[i]; }
;     if (tab != nullptr) {
;         const LAS float* tp = tab + k0 + (lane >> 5);
; #pragma unroll
;         for (int bp = 0; bp < 5; ++bp) { float s = 0.f;
; #pragma unroll
;             for (int i = 0; i < 32; ++i) s += tp[bp * 2048 + 2 * i] * wv_[i];
;             s += __shfl_xor(s, 32);
;             if (lane < 32) atomicAdd((unsigned long long*)(bias + (size_t)bp * ldb + n), (unsigned long long)(long long)(s * 4294967296.f)); }
	v_cndmask_b32_e32 v46, 0, v5, vcc
	v_cndmask_b32_e32 v47, 0, v43, vcc
	v_cndmask_b32_e32 v48, 0, v42, vcc
	ds_write2_b32 v13, v46, v47 offset1:66
	v_cndmask_b32_e32 v42, v48, v42, vcc
	v_cndmask_b32_e32 v43, v47, v43, vcc
	v_cndmask_b32_e32 v49, 0, v41, vcc
	v_cndmask_b32_e32 v50, 0, v40, vcc
	v_cndmask_b32_e32 v51, 0, v39, vcc
	v_cndmask_b32_e32 v52, 0, v38, vcc
	v_cndmask_b32_e32 v53, 0, v37, vcc
	v_cndmask_b32_e32 v54, 0, v36, vcc
	ds_write2_b32 v13, v48, v49 offset0:132 offset1:198
	v_cndmask_b32_e32 v37, v53, v37, vcc
	v_cndmask_b32_e32 v38, v52, v38, vcc
	v_cndmask_b32_e32 v39, v51, v39, vcc
	v_cndmask_b32_e32 v40, v50, v40, vcc
	v_cndmask_b32_e32 v41, v49, v41, vcc
	v_cndmask_b32_e32 v55, 0, v35, vcc
	v_cndmask_b32_e32 v56, 0, v34, vcc
	v_cndmask_b32_e32 v57, 0, v32, vcc
	v_cndmask_b32_e32 v58, 0, v31, vcc
	v_cndmask_b32_e32 v59, 0, v30, vcc
	v_cndmask_b32_e32 v60, 0, v29, vcc
	v_cndmask_b32_e32 v61, 0, v28, vcc
	v_cndmask_b32_e32 v62, 0, v27, vcc
	v_cndmask_b32_e32 v63, 0, v26, vcc
	v_cndmask_b32_e32 v64, 0, v25, vcc
	v_add_u32_e32 v6, 0x400, v13
	ds_write2_b32 v6, v50, v51 offset0:8 offset1:74
	ds_write2_b32 v6, v52, v53 offset0:140 offset1:206
	v_add_u32_e32 v6, 0x800, v13
	ds_write2_b32 v6, v54, v55 offset0:16 offset1:82
	ds_write2_b32 v6, v56, v57 offset0:148 offset1:214
	v_add_u32_e32 v6, 0xc00, v13
	ds_write2_b32 v6, v58, v59 offset0:24 offset1:90
	ds_write2_b32 v6, v60, v61 offset0:156 offset1:222
	v_add_u32_e32 v6, 0x1000, v13
	s_waitcnt vmcnt(12)
	v_cndmask_b32_e32 v65, 0, v24, vcc
	ds_write2_b32 v6, v62, v63 offset0:32 offset1:98
	ds_write2_b32 v6, v64, v65 offset0:164 offset1:230
	s_waitcnt vmcnt(11)
	v_cndmask_b32_e32 v66, 0, v23, vcc
	s_waitcnt vmcnt(10)
	v_cndmask_b32_e32 v67, 0, v22, vcc
	v_add_u32_e32 v6, 0x1400, v13
	ds_write2_b32 v6, v66, v67 offset0:40 offset1:106
	s_and_b32 s4, s14, 0xffffff00
	s_waitcnt vmcnt(9)
	v_cndmask_b32_e32 v68, 0, v21, vcc
	v_cndmask_b32_e32 v36, v54, v36, vcc
	v_cndmask_b32_e32 v35, v55, v35, vcc
	v_cndmask_b32_e32 v34, v56, v34, vcc
	v_cndmask_b32_e32 v32, v57, v32, vcc
	v_cndmask_b32_e32 v31, v58, v31, vcc
	v_cndmask_b32_e32 v30, v59, v30, vcc
	s_waitcnt vmcnt(8)
	v_cndmask_b32_e32 v69, 0, v20, vcc
	ds_write2_b32 v6, v68, v69 offset0:172 offset1:238
	v_add_u32_e32 v6, 0x1800, v13
	v_cndmask_b32_e32 v29, v60, v29, vcc
	v_cndmask_b32_e32 v28, v61, v28, vcc
	v_cndmask_b32_e32 v27, v62, v27, vcc
	v_cndmask_b32_e32 v26, v63, v26, vcc
	s_waitcnt vmcnt(7)
	v_cndmask_b32_e32 v70, 0, v19, vcc
	v_cndmask_b32_e32 v25, v64, v25, vcc
	v_cndmask_b32_e32 v24, v65, v24, vcc
	v_cndmask_b32_e32 v23, v66, v23, vcc
	v_cndmask_b32_e32 v22, v67, v22, vcc
	v_cndmask_b32_e32 v21, v68, v21, vcc
	v_cndmask_b32_e32 v20, v69, v20, vcc
	s_waitcnt vmcnt(6)
	v_cndmask_b32_e32 v71, 0, v18, vcc
	ds_write2_b32 v6, v70, v71 offset0:48 offset1:114
	v_cndmask_b32_e32 v19, v70, v19, vcc
	v_cndmask_b32_e32 v18, v71, v18, vcc
	s_waitcnt vmcnt(5)
	v_cndmask_b32_e32 v72, 0, v17, vcc
	v_cndmask_b32_e32 v17, v72, v17, vcc
	s_waitcnt vmcnt(4)
	v_cndmask_b32_e32 v73, 0, v16, vcc
	ds_write2_b32 v6, v72, v73 offset0:180 offset1:246
	v_cndmask_b32_e32 v16, v73, v16, vcc
	s_waitcnt vmcnt(3)
	v_cndmask_b32_e32 v15, 0, v44, vcc
	s_waitcnt vmcnt(2)
	v_cndmask_b32_e32 v74, 0, v45, vcc
	ds_write2_b32 v75, v15, v74 offset0:56 offset1:122
	v_cndmask_b32_e32 v15, v15, v44, vcc
	v_cndmask_b32_e32 v44, v46, v5, vcc
	v_ashrrev_i32_e32 v5, 31, v4
	v_lshl_add_u64 v[4:5], v[4:5], 3, s[8:9]
	s_waitcnt vmcnt(1)
	v_cndmask_b32_e32 v76, 0, v14, vcc
	v_cndmask_b32_e32 v6, v76, v14, vcc
	v_cndmask_b32_e32 v14, v74, v45, vcc
	s_waitcnt vmcnt(0)
	v_cndmask_b32_e32 v7, 0, v7, vcc
	ds_write2_b32 v75, v76, v7 offset0:188 offset1:254
	v_add_u32_e32 v45, s4, v9
	ds_read2_b32 v[46:47], v45 offset1:2
	ds_read2_b32 v[48:49], v45 offset0:4 offset1:6
	ds_read2_b32 v[50:51], v45 offset0:8 offset1:10
	ds_read2_b32 v[52:53], v45 offset0:12 offset1:14
	s_waitcnt lgkmcnt(3)
	v_fma_f32 v46, v46, v44, 0
	v_fmac_f32_e32 v46, v47, v43
	s_waitcnt lgkmcnt(2)
	v_fmac_f32_e32 v46, v48, v42
	v_fmac_f32_e32 v46, v49, v41
	ds_read2_b32 v[48:49], v45 offset0:16 offset1:18
	s_waitcnt lgkmcnt(2)
	v_fmac_f32_e32 v46, v50, v40
	v_fmac_f32_e32 v46, v51, v39
	s_waitcnt lgkmcnt(1)
	v_fmac_f32_e32 v46, v52, v38
	v_fmac_f32_e32 v46, v53, v37
	s_waitcnt lgkmcnt(0)
	v_fmac_f32_e32 v46, v48, v36
	v_fmac_f32_e32 v46, v49, v35
	ds_read2_b32 v[100:101], v45 offset0:20 offset1:22
	ds_read2_b32 v[102:103], v45 offset0:24 offset1:26
	ds_read2_b32 v[104:105], v45 offset0:28 offset1:30
	ds_read2_b32 v[106:107], v45 offset0:32 offset1:34
	ds_read2_b32 v[108:109], v45 offset0:36 offset1:38
	ds_read2_b32 v[110:111], v45 offset0:40 offset1:42
	ds_read2_b32 v[112:113], v45 offset0:44 offset1:46
	ds_read2_b32 v[114:115], v45 offset0:48 offset1:50
	ds_read2_b32 v[116:117], v45 offset0:52 offset1:54
	ds_read2_b32 v[118:119], v45 offset0:56 offset1:58
	ds_read2_b32 v[120:121], v45 offset0:60 offset1:62
	s_waitcnt lgkmcnt(10)
	v_fmac_f32_e32 v46, v100, v34
	v_fmac_f32_e32 v46, v101, v32
	s_waitcnt lgkmcnt(9)
	v_fmac_f32_e32 v46, v102, v31
	v_fmac_f32_e32 v46, v103, v30
	s_waitcnt lgkmcnt(8)
	v_fmac_f32_e32 v46, v104, v29
	v_fmac_f32_e32 v46, v105, v28
	s_waitcnt lgkmcnt(7)
	v_fmac_f32_e32 v46, v106, v27
	v_fmac_f32_e32 v46, v107, v26
	s_waitcnt lgkmcnt(6)
	v_fmac_f32_e32 v46, v108, v25
	v_fmac_f32_e32 v46, v109, v24
	s_waitcnt lgkmcnt(5)
	v_fmac_f32_e32 v46, v110, v23
	v_fmac_f32_e32 v46, v111, v22
	s_waitcnt lgkmcnt(4)
	v_fmac_f32_e32 v46, v112, v21
	v_fmac_f32_e32 v46, v113, v20
	s_waitcnt lgkmcnt(3)
	v_fmac_f32_e32 v46, v114, v19
	v_fmac_f32_e32 v46, v115, v18
	s_waitcnt lgkmcnt(2)
	v_fmac_f32_e32 v46, v116, v17
	v_fmac_f32_e32 v46, v117, v16
	s_waitcnt lgkmcnt(1)
	v_fmac_f32_e32 v46, v118, v15
	v_fmac_f32_e32 v46, v119, v14
	s_waitcnt lgkmcnt(0)
	v_fmac_f32_e32 v46, v120, v6
	v_fmac_f32_e32 v46, v121, v7
	ds_bpermute_b32 v47, v10, v46
	s_and_saveexec_b64 s[4:5], s[2:3]
	s_cbranch_execz .LBB0_473
	s_waitcnt lgkmcnt(0)
	v_add_f32_e32 v46, v46, v47
	v_mul_f32_e32 v46, 0x4f800000, v46
	v_trunc_f32_e32 v46, v46
	v_mul_f32_e64 v47, |v46|, s97
	v_floor_f32_e32 v47, v47
	v_fma_f32 v48, v47, s74, |v46|
	v_cvt_u32_f32_e32 v48, v48
	v_cvt_u32_f32_e32 v47, v47
	v_ashrrev_i32_e32 v49, 31, v46
	v_xor_b32_e32 v46, v48, v49
	v_xor_b32_e32 v47, v47, v49
	v_sub_co_u32_e32 v46, vcc, v46, v49
	s_nop 1
	v_subb_co_u32_e32 v47, vcc, v47, v49, vcc
	global_atomic_add_x2 v[4:5], v[46:47], off
; #define LAS __attribute__((address_space(3)))
; __device__ __forceinline__ void transpose_item(const float* W, int K, int N, int NP, bf16* WT, LAS float* scr, int item, int lane, const LAS float* tab, long long* bias, int ldb, const float* kscale = nullptr) {
;     ...
;     for (int i = 0; i < 32; ++i) { if (!okn) wv_[i] = 0.f; if (kscale != nullptr) wv_[i] *= kscale[k0 + 2 * i + (lane >> 5)]; scr[(2 * i + (lane >> 5)) * 33 + (lane & 31)] = wv_[i]; }
;     if (tab != nullptr) {
;         const LAS float* tp = tab + k0 + (lane >> 5);
; #pragma unroll
;         for (int bp = 0; bp < 5; ++bp) { float s = 0.f;
; #pragma unroll
;             for (int i = 0; i < 32; ++i) s += tp[bp * 2048 + 2 * i] * wv_[i];
;             s += __shfl_xor(s, 32);
;             if (lane < 32) atomicAdd((unsigned long long*)(bias + (size_t)bp * ldb + n), (unsigned long long)(long long)(s * 4294967296.f)); }
.LBB0_473:
	s_or_b64 exec, exec, s[4:5]
	v_add_u32_e32 v54, 0x2000, v45
	s_waitcnt lgkmcnt(0)
	ds_read2_b32 v[46:47], v54 offset1:2
	ds_read2_b32 v[48:49], v54 offset0:4 offset1:6
	ds_read2_b32 v[50:51], v54 offset0:8 offset1:10
	ds_read2_b32 v[52:53], v54 offset0:12 offset1:14
	s_waitcnt lgkmcnt(3)
	v_fma_f32 v46, v44, v46, 0
	v_fmac_f32_e32 v46, v43, v47
	s_waitcnt lgkmcnt(2)
	v_fmac_f32_e32 v46, v42, v48
	v_fmac_f32_e32 v46, v41, v49
	ds_read2_b32 v[48:49], v54 offset0:16 offset1:18
	s_waitcnt lgkmcnt(2)
	v_fmac_f32_e32 v46, v40, v50
	v_fmac_f32_e32 v46, v39, v51
	s_waitcnt lgkmcnt(1)
	v_fmac_f32_e32 v46, v38, v52
	v_fmac_f32_e32 v46, v37, v53
	s_waitcnt lgkmcnt(0)
	v_fmac_f32_e32 v46, v36, v48
	v_fmac_f32_e32 v46, v35, v49
	ds_read2_b32 v[100:101], v54 offset0:20 offset1:22
	ds_read2_b32 v[102:103], v54 offset0:24 offset1:26
	ds_read2_b32 v[104:105], v54 offset0:28 offset1:30
	ds_read2_b32 v[106:107], v54 offset0:32 offset1:34
	ds_read2_b32 v[108:109], v54 offset0:36 offset1:38
	ds_read2_b32 v[110:111], v54 offset0:40 offset1:42
	ds_read2_b32 v[112:113], v54 offset0:44 offset1:46
	ds_read2_b32 v[114:115], v54 offset0:48 offset1:50
	ds_read2_b32 v[116:117], v54 offset0:52 offset1:54
	ds_read2_b32 v[118:119], v54 offset0:56 offset1:58
	ds_read2_b32 v[120:121], v54 offset0:60 offset1:62
	s_waitcnt lgkmcnt(10)
	v_fmac_f32_e32 v46, v34, v100
	v_fmac_f32_e32 v46, v32, v101
	s_waitcnt lgkmcnt(9)
	v_fmac_f32_e32 v46, v31, v102
	v_fmac_f32_e32 v46, v30, v103
	s_waitcnt lgkmcnt(8)
	v_fmac_f32_e32 v46, v29, v104
	v_fmac_f32_e32 v46, v28, v105
	s_waitcnt lgkmcnt(7)
	v_fmac_f32_e32 v46, v27, v106
	v_fmac_f32_e32 v46, v26, v107
	s_waitcnt lgkmcnt(6)
	v_fmac_f32_e32 v46, v25, v108
	v_fmac_f32_e32 v46, v24, v109
	s_waitcnt lgkmcnt(5)
	v_fmac_f32_e32 v46, v23, v110
	v_fmac_f32_e32 v46, v22, v111
	s_waitcnt lgkmcnt(4)
	v_fmac_f32_e32 v46, v21, v112
	v_fmac_f32_e32 v46, v20, v113
	s_waitcnt lgkmcnt(3)
	v_fmac_f32_e32 v46, v19, v114
	v_fmac_f32_e32 v46, v18, v115
	s_waitcnt lgkmcnt(2)
	v_fmac_f32_e32 v46, v17, v116
	v_fmac_f32_e32 v46, v16, v117
	s_waitcnt lgkmcnt(1)
	v_fmac_f32_e32 v46, v15, v118
	v_fmac_f32_e32 v46, v14, v119
	s_waitcnt lgkmcnt(0)
	v_fmac_f32_e32 v46, v6, v120
	v_fmac_f32_e32 v46, v7, v121
	ds_bpermute_b32 v47, v10, v46
	s_and_saveexec_b64 s[4:5], s[2:3]
	s_cbranch_execz .LBB0_475
	s_waitcnt lgkmcnt(0)
	v_add_f32_e32 v46, v46, v47
	v_mul_f32_e32 v46, 0x4f800000, v46
	v_trunc_f32_e32 v46, v46
	v_mul_f32_e64 v47, |v46|, s97
	v_floor_f32_e32 v47, v47
	v_fma_f32 v48, v47, s74, |v46|
	v_cvt_u32_f32_e32 v48, v48
	v_cvt_u32_f32_e32 v47, v47
	v_ashrrev_i32_e32 v49, 31, v46
	v_xor_b32_e32 v46, v48, v49
	v_xor_b32_e32 v47, v47, v49
	v_sub_co_u32_e32 v46, vcc, v46, v49
	s_nop 1
	v_subb_co_u32_e32 v47, vcc, v47, v49, vcc
	v_add_co_u32_e32 v48, vcc, 0x17000, v4
	s_nop 1
	v_addc_co_u32_e32 v49, vcc, 0, v5, vcc
	global_atomic_add_x2 v[48:49], v[46:47], off offset:2048
.LBB0_475:
	s_or_b64 exec, exec, s[4:5]
	v_add_u32_e32 v54, 0x4000, v45
	s_waitcnt lgkmcnt(0)
	ds_read2_b32 v[46:47], v54 offset1:2
	ds_read2_b32 v[48:49], v54 offset0:4 offset1:6
	ds_read2_b32 v[50:51], v54 offset0:8 offset1:10
	ds_read2_b32 v[52:53], v54 offset0:12 offset1:14
	s_waitcnt lgkmcnt(3)
	v_fma_f32 v46, v44, v46, 0
	v_fmac_f32_e32 v46, v43, v47
	s_waitcnt lgkmcnt(2)
	v_fmac_f32_e32 v46, v42, v48
	v_fmac_f32_e32 v46, v41, v49
	ds_read2_b32 v[48:49], v54 offset0:16 offset1:18
	s_waitcnt lgkmcnt(2)
	v_fmac_f32_e32 v46, v40, v50
	v_fmac_f32_e32 v46, v39, v51
	s_waitcnt lgkmcnt(1)
	v_fmac_f32_e32 v46, v38, v52
	v_fmac_f32_e32 v46, v37, v53
	s_waitcnt lgkmcnt(0)
	v_fmac_f32_e32 v46, v36, v48
	v_fmac_f32_e32 v46, v35, v49
	ds_read2_b32 v[100:101], v54 offset0:20 offset1:22
	ds_read2_b32 v[102:103], v54 offset0:24 offset1:26
	ds_read2_b32 v[104:105], v54 offset0:28 offset1:30
	ds_read2_b32 v[106:107], v54 offset0:32 offset1:34
	ds_read2_b32 v[108:109], v54 offset0:36 offset1:38
	ds_read2_b32 v[110:111], v54 offset0:40 offset1:42
	ds_read2_b32 v[112:113], v54 offset0:44 offset1:46
	ds_read2_b32 v[114:115], v54 offset0:48 offset1:50
	ds_read2_b32 v[116:117], v54 offset0:52 offset1:54
	ds_read2_b32 v[118:119], v54 offset0:56 offset1:58
	ds_read2_b32 v[120:121], v54 offset0:60 offset1:62
	s_waitcnt lgkmcnt(10)
	v_fmac_f32_e32 v46, v34, v100
	v_fmac_f32_e32 v46, v32, v101
	s_waitcnt lgkmcnt(9)
	v_fmac_f32_e32 v46, v31, v102
	v_fmac_f32_e32 v46, v30, v103
	s_waitcnt lgkmcnt(8)
	v_fmac_f32_e32 v46, v29, v104
	v_fmac_f32_e32 v46, v28, v105
	s_waitcnt lgkmcnt(7)
	v_fmac_f32_e32 v46, v27, v106
	v_fmac_f32_e32 v46, v26, v107
	s_waitcnt lgkmcnt(6)
	v_fmac_f32_e32 v46, v25, v108
	v_fmac_f32_e32 v46, v24, v109
	s_waitcnt lgkmcnt(5)
	v_fmac_f32_e32 v46, v23, v110
	v_fmac_f32_e32 v46, v22, v111
	s_waitcnt lgkmcnt(4)
	v_fmac_f32_e32 v46, v21, v112
	v_fmac_f32_e32 v46, v20, v113
	s_waitcnt lgkmcnt(3)
	v_fmac_f32_e32 v46, v19, v114
	v_fmac_f32_e32 v46, v18, v115
	s_waitcnt lgkmcnt(2)
	v_fmac_f32_e32 v46, v17, v116
	v_fmac_f32_e32 v46, v16, v117
	s_waitcnt lgkmcnt(1)
	v_fmac_f32_e32 v46, v15, v118
	v_fmac_f32_e32 v46, v14, v119
	s_waitcnt lgkmcnt(0)
	v_fmac_f32_e32 v46, v6, v120
	v_fmac_f32_e32 v46, v7, v121
	ds_bpermute_b32 v47, v10, v46
	s_and_saveexec_b64 s[4:5], s[2:3]
	s_cbranch_execz .LBB0_477
	s_waitcnt lgkmcnt(0)
	v_add_f32_e32 v46, v46, v47
	v_mul_f32_e32 v46, 0x4f800000, v46
	v_trunc_f32_e32 v46, v46
	v_mul_f32_e64 v47, |v46|, s97
	v_floor_f32_e32 v47, v47
	v_fma_f32 v48, v47, s74, |v46|
	v_cvt_u32_f32_e32 v48, v48
	v_cvt_u32_f32_e32 v47, v47
	v_ashrrev_i32_e32 v49, 31, v46
	v_xor_b32_e32 v46, v48, v49
	v_xor_b32_e32 v47, v47, v49
	v_sub_co_u32_e32 v46, vcc, v46, v49
	s_nop 1
	v_subb_co_u32_e32 v47, vcc, v47, v49, vcc
	v_add_co_u32_e32 v48, vcc, 0x2f000, v4
	s_nop 1
	v_addc_co_u32_e32 v49, vcc, 0, v5, vcc
	global_atomic_add_x2 v[48:49], v[46:47], off
; #define LAS __attribute__((address_space(3)))
; __device__ __forceinline__ void transpose_item(const float* W, int K, int N, int NP, bf16* WT, LAS float* scr, int item, int lane, const LAS float* tab, long long* bias, int ldb, const float* kscale = nullptr) {
;     ...
;     for (int i = 0; i < 32; ++i) { if (!okn) wv_[i] = 0.f; if (kscale != nullptr) wv_[i] *= kscale[k0 + 2 * i + (lane >> 5)]; scr[(2 * i + (lane >> 5)) * 33 + (lane & 31)] = wv_[i]; }
;     if (tab != nullptr) {
;         const LAS float* tp = tab + k0 + (lane >> 5);
; #pragma unroll
;         for (int bp = 0; bp < 5; ++bp) { float s = 0.f;
; #pragma unroll
;             for (int i = 0; i < 32; ++i) s += tp[bp * 2048 + 2 * i] * wv_[i];
;             s += __shfl_xor(s, 32);
;             if (lane < 32) atomicAdd((unsigned long long*)(bias + (size_t)bp * ldb + n), (unsigned long long)(long long)(s * 4294967296.f)); }
.LBB0_477:
	s_or_b64 exec, exec, s[4:5]
	v_add_u32_e32 v54, 0x6000, v45
	s_waitcnt lgkmcnt(0)
	ds_read2_b32 v[46:47], v54 offset1:2
	ds_read2_b32 v[48:49], v54 offset0:4 offset1:6
	ds_read2_b32 v[50:51], v54 offset0:8 offset1:10
	ds_read2_b32 v[52:53], v54 offset0:12 offset1:14
	s_waitcnt lgkmcnt(3)
	v_fma_f32 v46, v44, v46, 0
	v_fmac_f32_e32 v46, v43, v47
	s_waitcnt lgkmcnt(2)
	v_fmac_f32_e32 v46, v42, v48
	v_fmac_f32_e32 v46, v41, v49
	ds_read2_b32 v[48:49], v54 offset0:16 offset1:18
	s_waitcnt lgkmcnt(2)
	v_fmac_f32_e32 v46, v40, v50
	v_fmac_f32_e32 v46, v39, v51
	s_waitcnt lgkmcnt(1)
	v_fmac_f32_e32 v46, v38, v52
	v_fmac_f32_e32 v46, v37, v53
	s_waitcnt lgkmcnt(0)
	v_fmac_f32_e32 v46, v36, v48
	v_fmac_f32_e32 v46, v35, v49
	ds_read2_b32 v[100:101], v54 offset0:20 offset1:22
	ds_read2_b32 v[102:103], v54 offset0:24 offset1:26
	ds_read2_b32 v[104:105], v54 offset0:28 offset1:30
	ds_read2_b32 v[106:107], v54 offset0:32 offset1:34
	ds_read2_b32 v[108:109], v54 offset0:36 offset1:38
	ds_read2_b32 v[110:111], v54 offset0:40 offset1:42
	ds_read2_b32 v[112:113], v54 offset0:44 offset1:46
	ds_read2_b32 v[114:115], v54 offset0:48 offset1:50
	ds_read2_b32 v[116:117], v54 offset0:52 offset1:54
	ds_read2_b32 v[118:119], v54 offset0:56 offset1:58
	ds_read2_b32 v[120:121], v54 offset0:60 offset1:62
	s_waitcnt lgkmcnt(10)
	v_fmac_f32_e32 v46, v34, v100
	v_fmac_f32_e32 v46, v32, v101
	s_waitcnt lgkmcnt(9)
	v_fmac_f32_e32 v46, v31, v102
	v_fmac_f32_e32 v46, v30, v103
	s_waitcnt lgkmcnt(8)
	v_fmac_f32_e32 v46, v29, v104
	v_fmac_f32_e32 v46, v28, v105
	s_waitcnt lgkmcnt(7)
	v_fmac_f32_e32 v46, v27, v106
	v_fmac_f32_e32 v46, v26, v107
	s_waitcnt lgkmcnt(6)
	v_fmac_f32_e32 v46, v25, v108
	v_fmac_f32_e32 v46, v24, v109
	s_waitcnt lgkmcnt(5)
	v_fmac_f32_e32 v46, v23, v110
	v_fmac_f32_e32 v46, v22, v111
	s_waitcnt lgkmcnt(4)
	v_fmac_f32_e32 v46, v21, v112
	v_fmac_f32_e32 v46, v20, v113
	s_waitcnt lgkmcnt(3)
	v_fmac_f32_e32 v46, v19, v114
	v_fmac_f32_e32 v46, v18, v115
	s_waitcnt lgkmcnt(2)
	v_fmac_f32_e32 v46, v17, v116
	v_fmac_f32_e32 v46, v16, v117
	s_waitcnt lgkmcnt(1)
	v_fmac_f32_e32 v46, v15, v118
	v_fmac_f32_e32 v46, v14, v119
	s_waitcnt lgkmcnt(0)
	v_fmac_f32_e32 v46, v6, v120
	v_fmac_f32_e32 v46, v7, v121
	ds_bpermute_b32 v47, v10, v46
	s_and_saveexec_b64 s[4:5], s[2:3]
	s_cbranch_execz .LBB0_479
	s_waitcnt lgkmcnt(0)
	v_add_f32_e32 v46, v46, v47
	v_mul_f32_e32 v46, 0x4f800000, v46
	v_trunc_f32_e32 v46, v46
	v_mul_f32_e64 v47, |v46|, s97
	v_floor_f32_e32 v47, v47
	v_fma_f32 v48, v47, s74, |v46|
	v_cvt_u32_f32_e32 v48, v48
	v_cvt_u32_f32_e32 v47, v47
	v_ashrrev_i32_e32 v49, 31, v46
	v_xor_b32_e32 v46, v48, v49
	v_xor_b32_e32 v47, v47, v49
	v_sub_co_u32_e32 v46, vcc, v46, v49
	s_nop 1
	v_subb_co_u32_e32 v47, vcc, v47, v49, vcc
	v_add_co_u32_e32 v48, vcc, 0x46000, v4
	s_nop 1
	v_addc_co_u32_e32 v49, vcc, 0, v5, vcc
	global_atomic_add_x2 v[48:49], v[46:47], off offset:2048
.LBB0_479:
	s_or_b64 exec, exec, s[4:5]
	v_add_u32_e32 v45, 0x8000, v45
	s_waitcnt lgkmcnt(0)
	ds_read2_b32 v[46:47], v45 offset1:2
	ds_read2_b32 v[48:49], v45 offset0:4 offset1:6
	ds_read2_b32 v[50:51], v45 offset0:8 offset1:10
	ds_read2_b32 v[52:53], v45 offset0:12 offset1:14
	s_waitcnt lgkmcnt(3)
	v_fma_f32 v44, v44, v46, 0
	v_fmac_f32_e32 v44, v43, v47
	s_waitcnt lgkmcnt(2)
	v_fmac_f32_e32 v44, v42, v48
	v_fmac_f32_e32 v44, v41, v49
	s_waitcnt lgkmcnt(1)
	v_fmac_f32_e32 v44, v40, v50
	v_fmac_f32_e32 v44, v39, v51
	s_waitcnt lgkmcnt(0)
	v_fmac_f32_e32 v44, v38, v52
	ds_read2_b32 v[38:39], v45 offset0:16 offset1:18
	v_fmac_f32_e32 v44, v37, v53
	s_waitcnt lgkmcnt(0)
	v_fmac_f32_e32 v44, v36, v38
	ds_read2_b32 v[36:37], v45 offset0:20 offset1:22
	v_fmac_f32_e32 v44, v35, v39
	s_waitcnt lgkmcnt(0)
	v_fmac_f32_e32 v44, v34, v36
	ds_read2_b32 v[34:35], v45 offset0:24 offset1:26
	v_fmac_f32_e32 v44, v32, v37
	s_waitcnt lgkmcnt(0)
	v_fmac_f32_e32 v44, v31, v34
	v_fmac_f32_e32 v44, v30, v35
	ds_read2_b32 v[100:101], v45 offset0:28 offset1:30
	ds_read2_b32 v[102:103], v45 offset0:32 offset1:34
	ds_read2_b32 v[104:105], v45 offset0:36 offset1:38
	ds_read2_b32 v[106:107], v45 offset0:40 offset1:42
	ds_read2_b32 v[108:109], v45 offset0:44 offset1:46
	ds_read2_b32 v[110:111], v45 offset0:48 offset1:50
	ds_read2_b32 v[112:113], v45 offset0:52 offset1:54
	ds_read2_b32 v[114:115], v45 offset0:56 offset1:58
	ds_read2_b32 v[116:117], v45 offset0:60 offset1:62
	s_waitcnt lgkmcnt(8)
	v_fmac_f32_e32 v44, v29, v100
	v_fmac_f32_e32 v44, v28, v101
	s_waitcnt lgkmcnt(7)
	v_fmac_f32_e32 v44, v27, v102
	v_fmac_f32_e32 v44, v26, v103
	s_waitcnt lgkmcnt(6)
	v_fmac_f32_e32 v44, v25, v104
	v_fmac_f32_e32 v44, v24, v105
	s_waitcnt lgkmcnt(5)
	v_fmac_f32_e32 v44, v23, v106
	v_fmac_f32_e32 v44, v22, v107
	s_waitcnt lgkmcnt(4)
	v_fmac_f32_e32 v44, v21, v108
	v_fmac_f32_e32 v44, v20, v109
	s_waitcnt lgkmcnt(3)
	v_fmac_f32_e32 v44, v19, v110
	v_fmac_f32_e32 v44, v18, v111
	s_waitcnt lgkmcnt(2)
	v_fmac_f32_e32 v44, v17, v112
	v_fmac_f32_e32 v44, v16, v113
	s_waitcnt lgkmcnt(1)
	v_fmac_f32_e32 v44, v15, v114
	v_fmac_f32_e32 v44, v14, v115
	s_waitcnt lgkmcnt(0)
	v_fmac_f32_e32 v44, v6, v116
	v_fmac_f32_e32 v44, v7, v117
	ds_bpermute_b32 v6, v10, v44
	s_and_saveexec_b64 s[4:5], s[2:3]
	s_cbranch_execz .LBB0_470
	s_waitcnt lgkmcnt(0)
	v_add_f32_e32 v6, v44, v6
	v_mul_f32_e32 v6, 0x4f800000, v6
	v_trunc_f32_e32 v6, v6
	v_mul_f32_e64 v7, |v6|, s97
	v_floor_f32_e32 v7, v7
	v_fma_f32 v14, v7, s74, |v6|
	v_cvt_u32_f32_e32 v14, v14
	v_cvt_u32_f32_e32 v7, v7
	v_ashrrev_i32_e32 v15, 31, v6
	v_xor_b32_e32 v6, v14, v15
	v_xor_b32_e32 v7, v7, v15
	v_sub_co_u32_e32 v6, vcc, v6, v15
	s_nop 1
	v_subb_co_u32_e32 v7, vcc, v7, v15, vcc
	v_add_co_u32_e32 v4, vcc, 0x5e000, v4
	s_nop 1
	v_addc_co_u32_e32 v5, vcc, 0, v5, vcc
	global_atomic_add_x2 v[4:5], v[6:7], off
	s_branch .LBB0_470

; __device__ __forceinline__ void transpose_item(const float* W, int K, int N, int NP, bf16* WT, LAS float* scr, int item, int lane, const LAS float* tab, long long* bias, int ldb, const float* kscale = nullptr) {
;     const int nblk = NP / 32, kb = item / nblk, nb = item - kb * nblk, k0 = 64 * kb, n0 = 32 * nb;
;     const int n = n0 + (lane & 31); const bool okn = n < N;
;     float wv_[32];
;     const float* wp = W + (size_t)(k0 + (lane >> 5)) * N + (okn ? n : 0);
; #pragma unroll
;     for (int i = 0; i < 32; ++i) wv_[i] = wp[(size_t)(2 * i) * N];
.LBB0_1355:
	s_ashr_i32 s3, s15, 31
	s_lshr_b32 s3, s3, 24
	s_add_i32 s13, s15, s3
	s_ashr_i32 s3, s13, 8
	s_lshl_b32 s12, s3, 6
	s_lshl_b32 s3, s3, 13
	s_sub_i32 s6, s16, s3
	v_add_u32_e32 v4, s6, v16
	v_or_b32_e32 v6, s12, v1
	v_cmp_gt_i32_e32 vcc, s93, v4
	v_ashrrev_i32_e32 v7, 31, v6
	v_lshlrev_b64 v[6:7], 15, v[6:7]
	v_cndmask_b32_e32 v18, 0, v4, vcc
	v_lshl_add_u64 v[6:7], s[8:9], 0, v[6:7]
	v_ashrrev_i32_e32 v19, 31, v18
	v_lshl_add_u64 v[6:7], v[18:19], 2, v[6:7]
	v_add_co_u32_e64 v18, s[6:7], s92, v6
	global_load_dword v5, v[6:7], off
	s_nop 0
	v_addc_co_u32_e64 v19, s[6:7], 0, v7, s[6:7]
	global_load_dword v47, v[18:19], off
	v_add_co_u32_e64 v18, s[6:7], s78, v6
	v_add_u32_e32 v79, 0x1c00, v17
	s_nop 0
	v_addc_co_u32_e64 v19, s[6:7], 0, v7, s[6:7]
	global_load_dword v46, v[18:19], off
	v_add_co_u32_e64 v18, s[6:7], s49, v6
	s_nop 1
	v_addc_co_u32_e64 v19, s[6:7], 0, v7, s[6:7]
	global_load_dword v45, v[18:19], off
	v_add_co_u32_e64 v18, s[6:7], s79, v6
	s_nop 1
	v_addc_co_u32_e64 v19, s[6:7], 0, v7, s[6:7]
	global_load_dword v44, v[18:19], off
	v_add_co_u32_e64 v18, s[6:7], s0, v6
	s_nop 1
	v_addc_co_u32_e64 v19, s[6:7], 0, v7, s[6:7]
	global_load_dword v43, v[18:19], off
	v_add_co_u32_e64 v18, s[6:7], s40, v6
	s_nop 0
	s_nop 0
	v_addc_co_u32_e64 v19, s[6:7], 0, v7, s[6:7]
	global_load_dword v42, v[18:19], off
	v_add_co_u32_e64 v18, s[6:7], s96, v6
	s_nop 0
	s_nop 0
	v_addc_co_u32_e64 v19, s[6:7], 0, v7, s[6:7]
	s_mov_b32 s6, 0x80000
	global_load_dword v41, v[18:19], off
	v_add_co_u32_e64 v18, s[6:7], s6, v6
	s_nop 0
	s_nop 0
	v_addc_co_u32_e64 v19, s[6:7], 0, v7, s[6:7]
	s_mov_b32 s6, 0x90000
	global_load_dword v40, v[18:19], off
	v_add_co_u32_e64 v18, s[6:7], s6, v6
	s_nop 1
	v_addc_co_u32_e64 v19, s[6:7], 0, v7, s[6:7]
	s_mov_b32 s6, 0xa0000
	global_load_dword v39, v[18:19], off
	v_add_co_u32_e64 v18, s[6:7], s6, v6
	s_nop 1
	v_addc_co_u32_e64 v19, s[6:7], 0, v7, s[6:7]
	s_mov_b32 s6, 0xb0000
	global_load_dword v38, v[18:19], off
	v_add_co_u32_e64 v18, s[6:7], s6, v6
	s_nop 1
	v_addc_co_u32_e64 v19, s[6:7], 0, v7, s[6:7]
	s_mov_b32 s6, 0xc0000
	global_load_dword v37, v[18:19], off
	v_add_co_u32_e64 v18, s[6:7], s6, v6
	s_nop 1
	v_addc_co_u32_e64 v19, s[6:7], 0, v7, s[6:7]
	s_mov_b32 s6, 0xd0000
	global_load_dword v36, v[18:19], off
	v_add_co_u32_e64 v18, s[6:7], s6, v6
	s_nop 1
	v_addc_co_u32_e64 v19, s[6:7], 0, v7, s[6:7]
	s_mov_b32 s6, 0xe0000
	global_load_dword v35, v[18:19], off
	v_add_co_u32_e64 v18, s[6:7], s6, v6
	s_nop 1
	v_addc_co_u32_e64 v19, s[6:7], 0, v7, s[6:7]
	s_mov_b32 s6, 0xf0000
	global_load_dword v34, v[18:19], off
	v_add_co_u32_e64 v18, s[6:7], s6, v6
	s_nop 0
	s_nop 0
	v_addc_co_u32_e64 v19, s[6:7], 0, v7, s[6:7]
	s_mov_b32 s6, 0x100000
	global_load_dword v32, v[18:19], off
	v_add_co_u32_e64 v18, s[6:7], s6, v6
	s_nop 0
	s_nop 0
	v_addc_co_u32_e64 v19, s[6:7], 0, v7, s[6:7]
	s_mov_b32 s6, 0x110000
	global_load_dword v31, v[18:19], off
	v_add_co_u32_e64 v18, s[6:7], s6, v6
	s_nop 0
	s_nop 0
	v_addc_co_u32_e64 v19, s[6:7], 0, v7, s[6:7]
	s_mov_b32 s6, 0x120000
	global_load_dword v30, v[18:19], off
	v_add_co_u32_e64 v18, s[6:7], s6, v6
	s_nop 0
	s_nop 0
	v_addc_co_u32_e64 v19, s[6:7], 0, v7, s[6:7]
	s_mov_b32 s6, 0x130000
	global_load_dword v29, v[18:19], off
	v_add_co_u32_e64 v18, s[6:7], s6, v6
	s_nop 0
	s_nop 0
	v_addc_co_u32_e64 v19, s[6:7], 0, v7, s[6:7]
	s_mov_b32 s6, 0x140000
	global_load_dword v28, v[18:19], off
	v_add_co_u32_e64 v18, s[6:7], s6, v6
	s_nop 0
	s_nop 0
	v_addc_co_u32_e64 v19, s[6:7], 0, v7, s[6:7]
	s_mov_b32 s6, 0x150000
	global_load_dword v27, v[18:19], off
	v_add_co_u32_e64 v18, s[6:7], s6, v6
	s_nop 1
	v_addc_co_u32_e64 v19, s[6:7], 0, v7, s[6:7]
	s_mov_b32 s6, 0x160000
	global_load_dword v26, v[18:19], off
	v_add_co_u32_e64 v18, s[6:7], s6, v6
	s_nop 1
	v_addc_co_u32_e64 v19, s[6:7], 0, v7, s[6:7]
	s_mov_b32 s6, 0x170000
	global_load_dword v25, v[18:19], off
	v_add_co_u32_e64 v18, s[6:7], s6, v6
	s_nop 1
	v_addc_co_u32_e64 v19, s[6:7], 0, v7, s[6:7]
	s_mov_b32 s6, 0x180000
	global_load_dword v24, v[18:19], off
	v_add_co_u32_e64 v18, s[6:7], s6, v6
	s_nop 1
	v_addc_co_u32_e64 v19, s[6:7], 0, v7, s[6:7]
	s_mov_b32 s6, 0x190000
	global_load_dword v23, v[18:19], off
	v_add_co_u32_e64 v18, s[6:7], s6, v6
	s_nop 1
	v_addc_co_u32_e64 v19, s[6:7], 0, v7, s[6:7]
	s_mov_b32 s6, 0x1a0000
	global_load_dword v22, v[18:19], off
	v_add_co_u32_e64 v18, s[6:7], s6, v6
	s_nop 1
	v_addc_co_u32_e64 v19, s[6:7], 0, v7, s[6:7]
	s_mov_b32 s6, 0x1b0000
	global_load_dword v21, v[18:19], off
	v_add_co_u32_e64 v18, s[6:7], s6, v6
	s_nop 1
	v_addc_co_u32_e64 v19, s[6:7], 0, v7, s[6:7]
	s_mov_b32 s6, 0x1c0000
	global_load_dword v20, v[18:19], off
	v_add_co_u32_e64 v18, s[6:7], s6, v6
	s_nop 1
	v_addc_co_u32_e64 v19, s[6:7], 0, v7, s[6:7]
	s_mov_b32 s6, 0x1d0000
	global_load_dword v48, v[18:19], off
	v_add_co_u32_e64 v18, s[6:7], s6, v6
	s_nop 1
	v_addc_co_u32_e64 v19, s[6:7], 0, v7, s[6:7]
	s_mov_b32 s6, 0x1e0000
	global_load_dword v49, v[18:19], off
	v_add_co_u32_e64 v18, s[6:7], s6, v6
	s_nop 1
	v_addc_co_u32_e64 v19, s[6:7], 0, v7, s[6:7]
	s_mov_b32 s6, 0x1f0000
	s_nop 0
	v_add_co_u32_e64 v6, s[6:7], s6, v6
	global_load_dword v18, v[18:19], off
	s_nop 0
	v_addc_co_u32_e64 v7, s[6:7], 0, v7, s[6:7]
	global_load_dword v7, v[6:7], off
	s_waitcnt vmcnt(0)
; #define LAS __attribute__((address_space(3)))
; __device__ __forceinline__ void transpose_item(const float* W, int K, int N, int NP, bf16* WT, LAS float* scr, int item, int lane, const LAS float* tab, long long* bias, int ldb, const float* kscale = nullptr) {
;     ...
;     for (int i = 0; i < 32; ++i) { if (!okn) wv_[i] = 0.f; if (kscale != nullptr) wv_[i] *= kscale[k0 + 2 * i + (lane >> 5)]; scr[(2 * i + (lane >> 5)) * 33 + (lane & 31)] = wv_[i]; }
;     if (tab != nullptr) {
;         const LAS float* tp = tab + k0 + (lane >> 5);
; #pragma unroll
;         for (int bp = 0; bp < 5; ++bp) { float s = 0.f;
; #pragma unroll
;             for (int i = 0; i < 32; ++i) s += tp[bp * 2048 + 2 * i] * wv_[i];
;             s += __shfl_xor(s, 32);
;             if (lane < 32) atomicAdd((unsigned long long*)(bias + (size_t)bp * ldb + n), (unsigned long long)(long long)(s * 4294967296.f)); }
	v_cndmask_b32_e32 v50, 0, v5, vcc
	v_cndmask_b32_e32 v51, 0, v47, vcc
	v_cndmask_b32_e32 v52, 0, v46, vcc
	ds_write2_b32 v17, v50, v51 offset1:66
	v_cndmask_b32_e32 v46, v52, v46, vcc
	v_cndmask_b32_e32 v47, v51, v47, vcc
	v_cndmask_b32_e32 v53, 0, v45, vcc
	v_cndmask_b32_e32 v54, 0, v44, vcc
	v_cndmask_b32_e32 v55, 0, v43, vcc
	v_cndmask_b32_e32 v56, 0, v42, vcc
	v_cndmask_b32_e32 v57, 0, v41, vcc
	v_cndmask_b32_e32 v58, 0, v40, vcc
	ds_write2_b32 v17, v52, v53 offset0:132 offset1:198
	v_cndmask_b32_e32 v41, v57, v41, vcc
	v_cndmask_b32_e32 v42, v56, v42, vcc
	v_cndmask_b32_e32 v43, v55, v43, vcc
	v_cndmask_b32_e32 v44, v54, v44, vcc
	v_cndmask_b32_e32 v45, v53, v45, vcc
	v_cndmask_b32_e32 v59, 0, v39, vcc
	v_cndmask_b32_e32 v60, 0, v38, vcc
	v_cndmask_b32_e32 v61, 0, v37, vcc
	v_cndmask_b32_e32 v62, 0, v36, vcc
	v_cndmask_b32_e32 v63, 0, v35, vcc
	v_cndmask_b32_e32 v64, 0, v34, vcc
	v_cndmask_b32_e32 v65, 0, v32, vcc
	v_cndmask_b32_e32 v66, 0, v31, vcc
	v_cndmask_b32_e32 v67, 0, v30, vcc
	v_cndmask_b32_e32 v68, 0, v29, vcc
	v_add_u32_e32 v6, 0x400, v17
	ds_write2_b32 v6, v54, v55 offset0:8 offset1:74
	ds_write2_b32 v6, v56, v57 offset0:140 offset1:206
	v_add_u32_e32 v6, 0x800, v17
	ds_write2_b32 v6, v58, v59 offset0:16 offset1:82
	ds_write2_b32 v6, v60, v61 offset0:148 offset1:214
	v_add_u32_e32 v6, 0xc00, v17
	ds_write2_b32 v6, v62, v63 offset0:24 offset1:90
	ds_write2_b32 v6, v64, v65 offset0:156 offset1:222
	v_add_u32_e32 v6, 0x1000, v17
	s_waitcnt vmcnt(12)
	v_cndmask_b32_e32 v69, 0, v28, vcc
	ds_write2_b32 v6, v66, v67 offset0:32 offset1:98
	ds_write2_b32 v6, v68, v69 offset0:164 offset1:230
	s_waitcnt vmcnt(11)
	v_cndmask_b32_e32 v70, 0, v27, vcc
	s_waitcnt vmcnt(10)
	v_cndmask_b32_e32 v71, 0, v26, vcc
	v_add_u32_e32 v6, 0x1400, v17
	ds_write2_b32 v6, v70, v71 offset0:40 offset1:106
	s_and_b32 s6, s13, 0xffffff00
	s_waitcnt vmcnt(9)
	v_cndmask_b32_e32 v72, 0, v25, vcc
	v_cndmask_b32_e32 v40, v58, v40, vcc
	v_cndmask_b32_e32 v39, v59, v39, vcc
	v_cndmask_b32_e32 v38, v60, v38, vcc
	v_cndmask_b32_e32 v37, v61, v37, vcc
	v_cndmask_b32_e32 v36, v62, v36, vcc
	v_cndmask_b32_e32 v35, v63, v35, vcc
	s_waitcnt vmcnt(8)
	v_cndmask_b32_e32 v73, 0, v24, vcc
	ds_write2_b32 v6, v72, v73 offset0:172 offset1:238
	v_add_u32_e32 v6, 0x1800, v17
	v_cndmask_b32_e32 v34, v64, v34, vcc
	v_cndmask_b32_e32 v32, v65, v32, vcc
	v_cndmask_b32_e32 v31, v66, v31, vcc
	v_cndmask_b32_e32 v30, v67, v30, vcc
	s_waitcnt vmcnt(7)
	v_cndmask_b32_e32 v74, 0, v23, vcc
	v_cndmask_b32_e32 v29, v68, v29, vcc
	v_cndmask_b32_e32 v28, v69, v28, vcc
	v_cndmask_b32_e32 v27, v70, v27, vcc
	v_cndmask_b32_e32 v26, v71, v26, vcc
	v_cndmask_b32_e32 v25, v72, v25, vcc
	v_cndmask_b32_e32 v24, v73, v24, vcc
	s_waitcnt vmcnt(6)
	v_cndmask_b32_e32 v75, 0, v22, vcc
	ds_write2_b32 v6, v74, v75 offset0:48 offset1:114
	v_cndmask_b32_e32 v23, v74, v23, vcc
	v_cndmask_b32_e32 v22, v75, v22, vcc
	s_waitcnt vmcnt(5)
	v_cndmask_b32_e32 v76, 0, v21, vcc
	v_cndmask_b32_e32 v21, v76, v21, vcc
	s_waitcnt vmcnt(4)
	v_cndmask_b32_e32 v77, 0, v20, vcc
	ds_write2_b32 v6, v76, v77 offset0:180 offset1:246
	v_cndmask_b32_e32 v20, v77, v20, vcc
	s_waitcnt vmcnt(3)
	v_cndmask_b32_e32 v19, 0, v48, vcc
	s_waitcnt vmcnt(2)
	v_cndmask_b32_e32 v78, 0, v49, vcc
	ds_write2_b32 v79, v19, v78 offset0:56 offset1:122
	v_cndmask_b32_e32 v19, v19, v48, vcc
	v_cndmask_b32_e32 v48, v50, v5, vcc
	v_ashrrev_i32_e32 v5, 31, v4
	v_lshl_add_u64 v[4:5], v[4:5], 3, s[10:11]
	s_waitcnt vmcnt(1)
	v_cndmask_b32_e32 v80, 0, v18, vcc
	v_cndmask_b32_e32 v6, v80, v18, vcc
	v_cndmask_b32_e32 v18, v78, v49, vcc
	s_waitcnt vmcnt(0)
	v_cndmask_b32_e32 v7, 0, v7, vcc
	ds_write2_b32 v79, v80, v7 offset0:188 offset1:254
	v_add_u32_e32 v49, s6, v12
	ds_read2_b32 v[50:51], v49 offset1:2
	ds_read2_b32 v[52:53], v49 offset0:4 offset1:6
	ds_read2_b32 v[54:55], v49 offset0:8 offset1:10
	ds_read2_b32 v[56:57], v49 offset0:12 offset1:14
	s_waitcnt lgkmcnt(3)
	v_fma_f32 v50, v50, v48, 0
	v_fmac_f32_e32 v50, v51, v47
	s_waitcnt lgkmcnt(2)
	v_fmac_f32_e32 v50, v52, v46
	v_fmac_f32_e32 v50, v53, v45
	ds_read2_b32 v[52:53], v49 offset0:16 offset1:18
	s_waitcnt lgkmcnt(2)
	v_fmac_f32_e32 v50, v54, v44
	v_fmac_f32_e32 v50, v55, v43
	s_waitcnt lgkmcnt(1)
	v_fmac_f32_e32 v50, v56, v42
	v_fmac_f32_e32 v50, v57, v41
	s_waitcnt lgkmcnt(0)
	v_fmac_f32_e32 v50, v52, v40
	v_fmac_f32_e32 v50, v53, v39
	ds_read2_b32 v[100:101], v49 offset0:20 offset1:22
	ds_read2_b32 v[102:103], v49 offset0:24 offset1:26
	ds_read2_b32 v[104:105], v49 offset0:28 offset1:30
	ds_read2_b32 v[106:107], v49 offset0:32 offset1:34
	ds_read2_b32 v[108:109], v49 offset0:36 offset1:38
	ds_read2_b32 v[110:111], v49 offset0:40 offset1:42
	ds_read2_b32 v[112:113], v49 offset0:44 offset1:46
	ds_read2_b32 v[114:115], v49 offset0:48 offset1:50
	ds_read2_b32 v[116:117], v49 offset0:52 offset1:54
	ds_read2_b32 v[118:119], v49 offset0:56 offset1:58
	ds_read2_b32 v[120:121], v49 offset0:60 offset1:62
	s_waitcnt lgkmcnt(10)
	v_fmac_f32_e32 v50, v100, v38
	v_fmac_f32_e32 v50, v101, v37
	s_waitcnt lgkmcnt(9)
	v_fmac_f32_e32 v50, v102, v36
	v_fmac_f32_e32 v50, v103, v35
	s_waitcnt lgkmcnt(8)
	v_fmac_f32_e32 v50, v104, v34
	v_fmac_f32_e32 v50, v105, v32
	s_waitcnt lgkmcnt(7)
	v_fmac_f32_e32 v50, v106, v31
	v_fmac_f32_e32 v50, v107, v30
	s_waitcnt lgkmcnt(6)
	v_fmac_f32_e32 v50, v108, v29
	v_fmac_f32_e32 v50, v109, v28
	s_waitcnt lgkmcnt(5)
	v_fmac_f32_e32 v50, v110, v27
	v_fmac_f32_e32 v50, v111, v26
	s_waitcnt lgkmcnt(4)
	v_fmac_f32_e32 v50, v112, v25
	v_fmac_f32_e32 v50, v113, v24
	s_waitcnt lgkmcnt(3)
	v_fmac_f32_e32 v50, v114, v23
	v_fmac_f32_e32 v50, v115, v22
	s_waitcnt lgkmcnt(2)
	v_fmac_f32_e32 v50, v116, v21
	v_fmac_f32_e32 v50, v117, v20
	s_waitcnt lgkmcnt(1)
	v_fmac_f32_e32 v50, v118, v19
	v_fmac_f32_e32 v50, v119, v18
	s_waitcnt lgkmcnt(0)
	v_fmac_f32_e32 v50, v120, v6
	v_fmac_f32_e32 v50, v121, v7
	ds_bpermute_b32 v51, v13, v50
	s_and_saveexec_b64 s[6:7], s[4:5]
	s_cbranch_execz .LBB0_1357
	s_waitcnt lgkmcnt(0)
	v_add_f32_e32 v50, v50, v51
	v_mul_f32_e32 v50, 0x4f800000, v50
	v_trunc_f32_e32 v50, v50
	v_mul_f32_e64 v51, |v50|, s97
	v_floor_f32_e32 v51, v51
	v_fma_f32 v52, v51, s74, |v50|
	v_cvt_u32_f32_e32 v52, v52
	v_cvt_u32_f32_e32 v51, v51
	v_ashrrev_i32_e32 v53, 31, v50
	v_xor_b32_e32 v50, v52, v53
	v_xor_b32_e32 v51, v51, v53
	v_sub_co_u32_e32 v50, vcc, v50, v53
	s_nop 1
	v_subb_co_u32_e32 v51, vcc, v51, v53, vcc
	global_atomic_add_x2 v[4:5], v[50:51], off
; #define LAS __attribute__((address_space(3)))
; __device__ __forceinline__ void transpose_item(const float* W, int K, int N, int NP, bf16* WT, LAS float* scr, int item, int lane, const LAS float* tab, long long* bias, int ldb, const float* kscale = nullptr) {
;     ...
;     for (int i = 0; i < 32; ++i) { if (!okn) wv_[i] = 0.f; if (kscale != nullptr) wv_[i] *= kscale[k0 + 2 * i + (lane >> 5)]; scr[(2 * i + (lane >> 5)) * 33 + (lane & 31)] = wv_[i]; }
;     if (tab != nullptr) {
;         const LAS float* tp = tab + k0 + (lane >> 5);
; #pragma unroll
;         for (int bp = 0; bp < 5; ++bp) { float s = 0.f;
; #pragma unroll
;             for (int i = 0; i < 32; ++i) s += tp[bp * 2048 + 2 * i] * wv_[i];
;             s += __shfl_xor(s, 32);
;             if (lane < 32) atomicAdd((unsigned long long*)(bias + (size_t)bp * ldb + n), (unsigned long long)(long long)(s * 4294967296.f)); }
.LBB0_1357:
	s_or_b64 exec, exec, s[6:7]
	v_add_u32_e32 v58, 0x2000, v49
	s_waitcnt lgkmcnt(0)
	ds_read2_b32 v[50:51], v58 offset1:2
	ds_read2_b32 v[52:53], v58 offset0:4 offset1:6
	ds_read2_b32 v[54:55], v58 offset0:8 offset1:10
	ds_read2_b32 v[56:57], v58 offset0:12 offset1:14
	s_waitcnt lgkmcnt(3)
	v_fma_f32 v50, v48, v50, 0
	v_fmac_f32_e32 v50, v47, v51
	s_waitcnt lgkmcnt(2)
	v_fmac_f32_e32 v50, v46, v52
	v_fmac_f32_e32 v50, v45, v53
	ds_read2_b32 v[52:53], v58 offset0:16 offset1:18
	s_waitcnt lgkmcnt(2)
	v_fmac_f32_e32 v50, v44, v54
	v_fmac_f32_e32 v50, v43, v55
	s_waitcnt lgkmcnt(1)
	v_fmac_f32_e32 v50, v42, v56
	v_fmac_f32_e32 v50, v41, v57
	s_waitcnt lgkmcnt(0)
	v_fmac_f32_e32 v50, v40, v52
	v_fmac_f32_e32 v50, v39, v53
	ds_read2_b32 v[100:101], v58 offset0:20 offset1:22
	ds_read2_b32 v[102:103], v58 offset0:24 offset1:26
	ds_read2_b32 v[104:105], v58 offset0:28 offset1:30
	ds_read2_b32 v[106:107], v58 offset0:32 offset1:34
	ds_read2_b32 v[108:109], v58 offset0:36 offset1:38
	ds_read2_b32 v[110:111], v58 offset0:40 offset1:42
	ds_read2_b32 v[112:113], v58 offset0:44 offset1:46
	ds_read2_b32 v[114:115], v58 offset0:48 offset1:50
	ds_read2_b32 v[116:117], v58 offset0:52 offset1:54
	ds_read2_b32 v[118:119], v58 offset0:56 offset1:58
	ds_read2_b32 v[120:121], v58 offset0:60 offset1:62
	s_waitcnt lgkmcnt(10)
	v_fmac_f32_e32 v50, v38, v100
	v_fmac_f32_e32 v50, v37, v101
	s_waitcnt lgkmcnt(9)
	v_fmac_f32_e32 v50, v36, v102
	v_fmac_f32_e32 v50, v35, v103
	s_waitcnt lgkmcnt(8)
	v_fmac_f32_e32 v50, v34, v104
	v_fmac_f32_e32 v50, v32, v105
	s_waitcnt lgkmcnt(7)
	v_fmac_f32_e32 v50, v31, v106
	v_fmac_f32_e32 v50, v30, v107
	s_waitcnt lgkmcnt(6)
	v_fmac_f32_e32 v50, v29, v108
	v_fmac_f32_e32 v50, v28, v109
	s_waitcnt lgkmcnt(5)
	v_fmac_f32_e32 v50, v27, v110
	v_fmac_f32_e32 v50, v26, v111
	s_waitcnt lgkmcnt(4)
	v_fmac_f32_e32 v50, v25, v112
	v_fmac_f32_e32 v50, v24, v113
	s_waitcnt lgkmcnt(3)
	v_fmac_f32_e32 v50, v23, v114
	v_fmac_f32_e32 v50, v22, v115
	s_waitcnt lgkmcnt(2)
	v_fmac_f32_e32 v50, v21, v116
	v_fmac_f32_e32 v50, v20, v117
	s_waitcnt lgkmcnt(1)
	v_fmac_f32_e32 v50, v19, v118
	v_fmac_f32_e32 v50, v18, v119
	s_waitcnt lgkmcnt(0)
	v_fmac_f32_e32 v50, v6, v120
	v_fmac_f32_e32 v50, v7, v121
	ds_bpermute_b32 v51, v13, v50
	s_and_saveexec_b64 s[6:7], s[4:5]
	s_cbranch_execz .LBB0_1359
	s_waitcnt lgkmcnt(0)
	v_add_f32_e32 v50, v50, v51
	v_mul_f32_e32 v50, 0x4f800000, v50
	v_trunc_f32_e32 v50, v50
	v_mul_f32_e64 v51, |v50|, s97
	v_floor_f32_e32 v51, v51
	v_fma_f32 v52, v51, s74, |v50|
	v_cvt_u32_f32_e32 v52, v52
	v_cvt_u32_f32_e32 v51, v51
	v_ashrrev_i32_e32 v53, 31, v50
	v_xor_b32_e32 v50, v52, v53
	v_xor_b32_e32 v51, v51, v53
	v_sub_co_u32_e32 v50, vcc, v50, v53
	s_nop 1
	v_subb_co_u32_e32 v51, vcc, v51, v53, vcc
	v_add_co_u32_e32 v52, vcc, 0x17000, v4
	s_nop 1
	v_addc_co_u32_e32 v53, vcc, 0, v5, vcc
	global_atomic_add_x2 v[52:53], v[50:51], off offset:2048
.LBB0_1359:
	s_or_b64 exec, exec, s[6:7]
	v_add_u32_e32 v58, 0x4000, v49
	s_waitcnt lgkmcnt(0)
	ds_read2_b32 v[50:51], v58 offset1:2
	ds_read2_b32 v[52:53], v58 offset0:4 offset1:6
	ds_read2_b32 v[54:55], v58 offset0:8 offset1:10
	ds_read2_b32 v[56:57], v58 offset0:12 offset1:14
	s_waitcnt lgkmcnt(3)
	v_fma_f32 v50, v48, v50, 0
	v_fmac_f32_e32 v50, v47, v51
	s_waitcnt lgkmcnt(2)
	v_fmac_f32_e32 v50, v46, v52
	v_fmac_f32_e32 v50, v45, v53
	ds_read2_b32 v[52:53], v58 offset0:16 offset1:18
	s_waitcnt lgkmcnt(2)
	v_fmac_f32_e32 v50, v44, v54
	v_fmac_f32_e32 v50, v43, v55
	s_waitcnt lgkmcnt(1)
	v_fmac_f32_e32 v50, v42, v56
	v_fmac_f32_e32 v50, v41, v57
	s_waitcnt lgkmcnt(0)
	v_fmac_f32_e32 v50, v40, v52
	v_fmac_f32_e32 v50, v39, v53
	ds_read2_b32 v[100:101], v58 offset0:20 offset1:22
	ds_read2_b32 v[102:103], v58 offset0:24 offset1:26
	ds_read2_b32 v[104:105], v58 offset0:28 offset1:30
	ds_read2_b32 v[106:107], v58 offset0:32 offset1:34
	ds_read2_b32 v[108:109], v58 offset0:36 offset1:38
	ds_read2_b32 v[110:111], v58 offset0:40 offset1:42
	ds_read2_b32 v[112:113], v58 offset0:44 offset1:46
	ds_read2_b32 v[114:115], v58 offset0:48 offset1:50
	ds_read2_b32 v[116:117], v58 offset0:52 offset1:54
	ds_read2_b32 v[118:119], v58 offset0:56 offset1:58
	ds_read2_b32 v[120:121], v58 offset0:60 offset1:62
	s_waitcnt lgkmcnt(10)
	v_fmac_f32_e32 v50, v38, v100
	v_fmac_f32_e32 v50, v37, v101
	s_waitcnt lgkmcnt(9)
	v_fmac_f32_e32 v50, v36, v102
	v_fmac_f32_e32 v50, v35, v103
	s_waitcnt lgkmcnt(8)
	v_fmac_f32_e32 v50, v34, v104
	v_fmac_f32_e32 v50, v32, v105
	s_waitcnt lgkmcnt(7)
	v_fmac_f32_e32 v50, v31, v106
	v_fmac_f32_e32 v50, v30, v107
	s_waitcnt lgkmcnt(6)
	v_fmac_f32_e32 v50, v29, v108
	v_fmac_f32_e32 v50, v28, v109
	s_waitcnt lgkmcnt(5)
	v_fmac_f32_e32 v50, v27, v110
	v_fmac_f32_e32 v50, v26, v111
	s_waitcnt lgkmcnt(4)
	v_fmac_f32_e32 v50, v25, v112
	v_fmac_f32_e32 v50, v24, v113
	s_waitcnt lgkmcnt(3)
	v_fmac_f32_e32 v50, v23, v114
	v_fmac_f32_e32 v50, v22, v115
	s_waitcnt lgkmcnt(2)
	v_fmac_f32_e32 v50, v21, v116
	v_fmac_f32_e32 v50, v20, v117
	s_waitcnt lgkmcnt(1)
	v_fmac_f32_e32 v50, v19, v118
	v_fmac_f32_e32 v50, v18, v119
	s_waitcnt lgkmcnt(0)
	v_fmac_f32_e32 v50, v6, v120
	v_fmac_f32_e32 v50, v7, v121
	ds_bpermute_b32 v51, v13, v50
	s_and_saveexec_b64 s[6:7], s[4:5]
	s_cbranch_execz .LBB0_1361
	s_waitcnt lgkmcnt(0)
	v_add_f32_e32 v50, v50, v51
	v_mul_f32_e32 v50, 0x4f800000, v50
	v_trunc_f32_e32 v50, v50
	v_mul_f32_e64 v51, |v50|, s97
	v_floor_f32_e32 v51, v51
	v_fma_f32 v52, v51, s74, |v50|
	v_cvt_u32_f32_e32 v52, v52
	v_cvt_u32_f32_e32 v51, v51
	v_ashrrev_i32_e32 v53, 31, v50
	v_xor_b32_e32 v50, v52, v53
	v_xor_b32_e32 v51, v51, v53
	v_sub_co_u32_e32 v50, vcc, v50, v53
	s_nop 1
	v_subb_co_u32_e32 v51, vcc, v51, v53, vcc
	v_add_co_u32_e32 v52, vcc, 0x2f000, v4
	s_nop 1
	v_addc_co_u32_e32 v53, vcc, 0, v5, vcc
	global_atomic_add_x2 v[52:53], v[50:51], off
; #define LAS __attribute__((address_space(3)))
; __device__ __forceinline__ void transpose_item(const float* W, int K, int N, int NP, bf16* WT, LAS float* scr, int item, int lane, const LAS float* tab, long long* bias, int ldb, const float* kscale = nullptr) {
;     ...
;     if (tab != nullptr) {
;         const LAS float* tp = tab + k0 + (lane >> 5);
; #pragma unroll
;         for (int bp = 0; bp < 5; ++bp) { float s = 0.f;
; #pragma unroll
;             for (int i = 0; i < 32; ++i) s += tp[bp * 2048 + 2 * i] * wv_[i];
;             s += __shfl_xor(s, 32);
;             if (lane < 32) atomicAdd((unsigned long long*)(bias + (size_t)bp * ldb + n), (unsigned long long)(long long)(s * 4294967296.f)); }
.LBB0_1361:
	s_or_b64 exec, exec, s[6:7]
	v_add_u32_e32 v58, 0x6000, v49
	s_waitcnt lgkmcnt(0)
	ds_read2_b32 v[50:51], v58 offset1:2
	ds_read2_b32 v[52:53], v58 offset0:4 offset1:6
	ds_read2_b32 v[54:55], v58 offset0:8 offset1:10
	ds_read2_b32 v[56:57], v58 offset0:12 offset1:14
	s_waitcnt lgkmcnt(3)
	v_fma_f32 v50, v48, v50, 0
	v_fmac_f32_e32 v50, v47, v51
	s_waitcnt lgkmcnt(2)
	v_fmac_f32_e32 v50, v46, v52
	v_fmac_f32_e32 v50, v45, v53
	ds_read2_b32 v[52:53], v58 offset0:16 offset1:18
	s_waitcnt lgkmcnt(2)
	v_fmac_f32_e32 v50, v44, v54
	v_fmac_f32_e32 v50, v43, v55
	s_waitcnt lgkmcnt(1)
	v_fmac_f32_e32 v50, v42, v56
	v_fmac_f32_e32 v50, v41, v57
	s_waitcnt lgkmcnt(0)
	v_fmac_f32_e32 v50, v40, v52
	v_fmac_f32_e32 v50, v39, v53
	ds_read2_b32 v[100:101], v58 offset0:20 offset1:22
	ds_read2_b32 v[102:103], v58 offset0:24 offset1:26
	ds_read2_b32 v[104:105], v58 offset0:28 offset1:30
	ds_read2_b32 v[106:107], v58 offset0:32 offset1:34
	ds_read2_b32 v[108:109], v58 offset0:36 offset1:38
	ds_read2_b32 v[110:111], v58 offset0:40 offset1:42
	ds_read2_b32 v[112:113], v58 offset0:44 offset1:46
	ds_read2_b32 v[114:115], v58 offset0:48 offset1:50
	ds_read2_b32 v[116:117], v58 offset0:52 offset1:54
	ds_read2_b32 v[118:119], v58 offset0:56 offset1:58
	ds_read2_b32 v[120:121], v58 offset0:60 offset1:62
	s_waitcnt lgkmcnt(10)
	v_fmac_f32_e32 v50, v38, v100
	v_fmac_f32_e32 v50, v37, v101
	s_waitcnt lgkmcnt(9)
	v_fmac_f32_e32 v50, v36, v102
	v_fmac_f32_e32 v50, v35, v103
	s_waitcnt lgkmcnt(8)
	v_fmac_f32_e32 v50, v34, v104
	v_fmac_f32_e32 v50, v32, v105
	s_waitcnt lgkmcnt(7)
	v_fmac_f32_e32 v50, v31, v106
	v_fmac_f32_e32 v50, v30, v107
	s_waitcnt lgkmcnt(6)
	v_fmac_f32_e32 v50, v29, v108
	v_fmac_f32_e32 v50, v28, v109
	s_waitcnt lgkmcnt(5)
	v_fmac_f32_e32 v50, v27, v110
	v_fmac_f32_e32 v50, v26, v111
	s_waitcnt lgkmcnt(4)
	v_fmac_f32_e32 v50, v25, v112
	v_fmac_f32_e32 v50, v24, v113
	s_waitcnt lgkmcnt(3)
	v_fmac_f32_e32 v50, v23, v114
	v_fmac_f32_e32 v50, v22, v115
	s_waitcnt lgkmcnt(2)
	v_fmac_f32_e32 v50, v21, v116
	v_fmac_f32_e32 v50, v20, v117
	s_waitcnt lgkmcnt(1)
	v_fmac_f32_e32 v50, v19, v118
	v_fmac_f32_e32 v50, v18, v119
	s_waitcnt lgkmcnt(0)
	v_fmac_f32_e32 v50, v6, v120
	v_fmac_f32_e32 v50, v7, v121
	ds_bpermute_b32 v51, v13, v50
	s_and_saveexec_b64 s[6:7], s[4:5]
	s_cbranch_execz .LBB0_1363
	s_waitcnt lgkmcnt(0)
	v_add_f32_e32 v50, v50, v51
	v_mul_f32_e32 v50, 0x4f800000, v50
	v_trunc_f32_e32 v50, v50
	v_mul_f32_e64 v51, |v50|, s97
	v_floor_f32_e32 v51, v51
	v_fma_f32 v52, v51, s74, |v50|
	v_cvt_u32_f32_e32 v52, v52
	v_cvt_u32_f32_e32 v51, v51
	v_ashrrev_i32_e32 v53, 31, v50
	v_xor_b32_e32 v50, v52, v53
	v_xor_b32_e32 v51, v51, v53
	v_sub_co_u32_e32 v50, vcc, v50, v53
	s_nop 1
	v_subb_co_u32_e32 v51, vcc, v51, v53, vcc
	v_add_co_u32_e32 v52, vcc, 0x46000, v4
	s_nop 1
	v_addc_co_u32_e32 v53, vcc, 0, v5, vcc
	global_atomic_add_x2 v[52:53], v[50:51], off offset:2048
.LBB0_1363:
	s_or_b64 exec, exec, s[6:7]
	v_add_u32_e32 v49, 0x8000, v49
	s_waitcnt lgkmcnt(0)
	ds_read2_b32 v[50:51], v49 offset1:2
	ds_read2_b32 v[52:53], v49 offset0:4 offset1:6
	ds_read2_b32 v[54:55], v49 offset0:8 offset1:10
	ds_read2_b32 v[56:57], v49 offset0:12 offset1:14
	s_waitcnt lgkmcnt(3)
	v_fma_f32 v48, v48, v50, 0
	v_fmac_f32_e32 v48, v47, v51
	s_waitcnt lgkmcnt(2)
	v_fmac_f32_e32 v48, v46, v52
	v_fmac_f32_e32 v48, v45, v53
	s_waitcnt lgkmcnt(1)
	v_fmac_f32_e32 v48, v44, v54
	v_fmac_f32_e32 v48, v43, v55
	s_waitcnt lgkmcnt(0)
	v_fmac_f32_e32 v48, v42, v56
	ds_read2_b32 v[42:43], v49 offset0:16 offset1:18
	v_fmac_f32_e32 v48, v41, v57
	s_waitcnt lgkmcnt(0)
	v_fmac_f32_e32 v48, v40, v42
	ds_read2_b32 v[40:41], v49 offset0:20 offset1:22
	v_fmac_f32_e32 v48, v39, v43
	s_waitcnt lgkmcnt(0)
	v_fmac_f32_e32 v48, v38, v40
	ds_read2_b32 v[38:39], v49 offset0:24 offset1:26
	v_fmac_f32_e32 v48, v37, v41
	s_waitcnt lgkmcnt(0)
	v_fmac_f32_e32 v48, v36, v38
	ds_read2_b32 v[36:37], v49 offset0:28 offset1:30
	v_fmac_f32_e32 v48, v35, v39
	s_waitcnt lgkmcnt(0)
	v_fmac_f32_e32 v48, v34, v36
	ds_read2_b32 v[34:35], v49 offset0:32 offset1:34
	v_fmac_f32_e32 v48, v32, v37
	s_waitcnt lgkmcnt(0)
	v_fmac_f32_e32 v48, v31, v34
	v_fmac_f32_e32 v48, v30, v35
	ds_read2_b32 v[100:101], v49 offset0:36 offset1:38
	ds_read2_b32 v[102:103], v49 offset0:40 offset1:42
	ds_read2_b32 v[104:105], v49 offset0:44 offset1:46
	ds_read2_b32 v[106:107], v49 offset0:48 offset1:50
	ds_read2_b32 v[108:109], v49 offset0:52 offset1:54
	ds_read2_b32 v[110:111], v49 offset0:56 offset1:58
	ds_read2_b32 v[112:113], v49 offset0:60 offset1:62
	s_waitcnt lgkmcnt(6)
	v_fmac_f32_e32 v48, v29, v100
	v_fmac_f32_e32 v48, v28, v101
	s_waitcnt lgkmcnt(5)
	v_fmac_f32_e32 v48, v27, v102
	v_fmac_f32_e32 v48, v26, v103
	s_waitcnt lgkmcnt(4)
	v_fmac_f32_e32 v48, v25, v104
	v_fmac_f32_e32 v48, v24, v105
	s_waitcnt lgkmcnt(3)
	v_fmac_f32_e32 v48, v23, v106
	v_fmac_f32_e32 v48, v22, v107
	s_waitcnt lgkmcnt(2)
	v_fmac_f32_e32 v48, v21, v108
	v_fmac_f32_e32 v48, v20, v109
	s_waitcnt lgkmcnt(1)
	v_fmac_f32_e32 v48, v19, v110
	v_fmac_f32_e32 v48, v18, v111
	s_waitcnt lgkmcnt(0)
	v_fmac_f32_e32 v48, v6, v112
	v_fmac_f32_e32 v48, v7, v113
	ds_bpermute_b32 v6, v13, v48
	s_and_saveexec_b64 s[6:7], s[4:5]
	s_cbranch_execz .LBB0_1354
	s_waitcnt lgkmcnt(0)
	v_add_f32_e32 v6, v48, v6
	v_mul_f32_e32 v6, 0x4f800000, v6
	v_trunc_f32_e32 v6, v6
	v_mul_f32_e64 v7, |v6|, s97
	v_floor_f32_e32 v7, v7
	v_fma_f32 v18, v7, s74, |v6|
	v_cvt_u32_f32_e32 v18, v18
	v_cvt_u32_f32_e32 v7, v7
	v_ashrrev_i32_e32 v19, 31, v6
	v_xor_b32_e32 v6, v18, v19
	v_xor_b32_e32 v7, v7, v19
	v_sub_co_u32_e32 v6, vcc, v6, v19
	s_nop 1
	v_subb_co_u32_e32 v7, vcc, v7, v19, vcc
	v_add_co_u32_e32 v4, vcc, 0x5e000, v4
	s_nop 1
	v_addc_co_u32_e32 v5, vcc, 0, v5, vcc
	global_atomic_add_x2 v[4:5], v[6:7], off
	s_branch .LBB0_1354
